# v93 plus: code prefetch at kernel entry (8 KB) and 80 KB at seam 1, gMLP weight copy (256 KB) touched at seam 2
# baseline (speedup 1.0000x reference)
.LBB0_2:
	v_lshrrev_b32_e32 v1, 6, v0
	v_cmp_eq_u32_e32 vcc, 5, v1
	s_and_saveexec_b64 s[6:7], vcc
	s_cbranch_execz .Lipf_start
	s_getpc_b64 s[4:5]
	v_and_b32_e32 v2, 63, v0
	v_lshlrev_b32_e32 v1, 7, v2
	global_load_dword v251, v1, s[4:5]
.Lipf_start:
	s_or_b64 exec, exec, s[6:7]
	v_lshl_add_u32 v1, v0, 2, 0
	v_add_u32_e32 v1, 0x20000, v1
	v_mov_b32_e32 v2, 0
	ds_write2st64_b32 v1, v2, v2 offset1:8
	ds_write2st64_b32 v1, v2, v2 offset0:16 offset1:24
	v_or_b32_e32 v1, 0x800, v0
	s_mov_b64 s[4:5], -1
	s_and_saveexec_b64 s[6:7], s[4:5]
	v_lshl_add_u32 v3, v1, 2, 0
	v_add_u32_e32 v3, 0x20000, v3
	ds_write_b32 v3, v2
	s_or_b64 exec, exec, s[6:7]
	s_load_dwordx2 s[44:45], s[0:1], 0xa0
	s_load_dwordx8 s[80:87], s[0:1], 0x80
	s_and_saveexec_b64 s[6:7], s[4:5]
	s_add_i32 s2, 0, 0x20000
	v_lshl_add_u32 v1, v1, 2, s2
	v_mov_b32_e32 v2, 0
	ds_write_b32 v1, v2 offset:2048
	s_or_b64 exec, exec, s[6:7]
	s_load_dwordx2 s[94:95], s[0:1], 0xa8
	v_or_b32_e32 v1, 0xc00, v0
	v_cmp_gt_u32_e64 s[4:5], 7, 6
	v_cmp_gt_u32_e64 s[2:3], 7, 5
	s_and_saveexec_b64 s[6:7], s[2:3]
	v_lshl_add_u32 v2, v1, 2, 0
	v_add_u32_e32 v2, 0x20000, v2
	v_mov_b32_e32 v3, 0
	ds_write_b32 v2, v3
	s_or_b64 exec, exec, s[6:7]
	s_and_saveexec_b64 s[6:7], s[4:5]
	s_add_i32 s2, 0, 0x20000
	v_lshl_add_u32 v1, v1, 2, s2
	v_mov_b32_e32 v2, 0
	ds_write_b32 v1, v2 offset:2048
	s_or_b64 exec, exec, s[6:7]
	s_waitcnt lgkmcnt(0)
	s_add_u32 s70, s44, 0x1000
	s_addc_u32 s71, s45, 0
	s_sub_i32 s2, s95, s94
	s_mov_b32 s3, 0
	v_writelane_b32 v253, s3, 2
	s_cmp_lt_i32 s2, 2
	v_cmp_eq_u32_e32 vcc, 0, v0
	s_mov_b32 s2, 0
	s_barrier
	v_writelane_b32 v253, s2, 3
	s_cbranch_scc1 .LBB0_15
	s_getreg_b32 s2, hwreg(HW_REG_XCC_ID, 0, 4)
	s_and_b32 s2, s2, 15
	v_writelane_b32 v253, s2, 2
	s_and_saveexec_b64 s[4:5], vcc
	s_cbranch_execz .LBB0_14
	s_mov_b64 s[6:7], exec
	v_mbcnt_lo_u32_b32 v1, s6, 0
	v_mbcnt_hi_u32_b32 v1, s7, v1
	v_cmp_eq_u32_e32 vcc, 0, v1
	s_and_b64 s[2:3], exec, vcc
	s_mov_b64 exec, s[2:3]
	s_cbranch_execz .LBB0_14
	v_readlane_b32 s2, v253, 2
	s_lshl_b32 s2, s2, 8
	s_bcnt1_i32_b64 s3, s[6:7]
	v_mov_b32_e32 v1, s2
	v_mov_b32_e32 v2, s3
	global_atomic_add v1, v2, s[70:71] offset:1024

.LBB0_112:
	s_cmp_gt_i32 s95, 2
	s_cselect_b64 s[4:5], -1, 0
	s_and_b64 s[0:1], s[12:13], s[4:5]
	s_and_b64 vcc, exec, s[0:1]
	s_cbranch_vccz .LBB0_162
	s_waitcnt vmcnt(0)
	v_cmp_eq_u32_e32 vcc, 0, v0
	s_waitcnt lgkmcnt(0)
	s_barrier
	v_lshrrev_b32_e32 v1, 6, v0
	v_and_b32_e32 v2, 63, v0
	v_cmp_eq_u32_e32 vcc, 5, v1
	s_and_saveexec_b64 s[8:9], vcc
	s_cbranch_execz .Lipf1
	s_getpc_b64 s[2:3]
	v_lshlrev_b32_e32 v1, 7, v2
	global_load_dword v3, v1, s[2:3]
	s_add_u32 s2, s2, 0x2000
	s_addc_u32 s3, s3, 0
	global_load_dword v3, v1, s[2:3]
	s_add_u32 s2, s2, 0x2000
	s_addc_u32 s3, s3, 0
	global_load_dword v3, v1, s[2:3]
	s_add_u32 s2, s2, 0x2000
	s_addc_u32 s3, s3, 0
	global_load_dword v3, v1, s[2:3]
	s_add_u32 s2, s2, 0x2000
	s_addc_u32 s3, s3, 0
	global_load_dword v3, v1, s[2:3]
	s_add_u32 s2, s2, 0x2000
	s_addc_u32 s3, s3, 0
	global_load_dword v3, v1, s[2:3]
	s_add_u32 s2, s2, 0x2000
	s_addc_u32 s3, s3, 0
	global_load_dword v3, v1, s[2:3]
	s_add_u32 s2, s2, 0x2000
	s_addc_u32 s3, s3, 0
	global_load_dword v3, v1, s[2:3]
	s_add_u32 s2, s2, 0x2000
	s_addc_u32 s3, s3, 0
	global_load_dword v3, v1, s[2:3]
	s_add_u32 s2, s2, 0x2000
	s_addc_u32 s3, s3, 0
	global_load_dword v3, v1, s[2:3]

.LBB0_706:
	s_cmp_gt_i32 s95, 3
	s_cselect_b64 s[0:1], -1, 0
	s_and_b64 s[2:3], s[48:49], s[0:1]
	v_readlane_b32 s80, v253, 21
	s_andn2_b64 vcc, exec, s[2:3]
	v_readlane_b32 s81, v253, 22
	v_readlane_b32 s82, v253, 3
	v_readlane_b32 s60, v253, 36
	s_cbranch_vccnz .LBB0_756
	s_waitcnt vmcnt(0)
	v_cmp_eq_u32_e32 vcc, 0, v0
	s_waitcnt vmcnt(63) expcnt(7) lgkmcnt(15)
	s_barrier
	v_lshrrev_b32_e32 v1, 6, v0
	v_and_b32_e32 v2, 63, v0
	v_cmp_eq_u32_e32 vcc, 6, v1
	v_readlane_b32 s2, v253, 20
	s_and_saveexec_b64 s[8:9], vcc
	s_cbranch_execz .Lwsbpf
	s_nop 1
	s_cmp_lt_u32 s2, 32
	s_cbranch_scc0 .Lwsbpf
	s_lshl_b32 s2, s2, 13
	v_lshl_add_u32 v1, v2, 7, s2
	s_add_u32 s2, s44, 0x1e00000
	s_addc_u32 s3, s45, 0
	global_load_dword v3, v1, s[2:3]
.Lwsbpf:
	s_or_b64 exec, exec, s[8:9]
	v_cmp_eq_u32_e32 vcc, 0, v0
	v_lshrrev_b32_e32 v1, 6, v0
	v_and_b32_e32 v2, 63, v0
	v_cmp_eq_u32_e32 vcc, 5, v1
	s_and_saveexec_b64 s[8:9], vcc
	s_cbranch_execz .Lipf2
	s_getpc_b64 s[2:3]
	v_lshlrev_b32_e32 v1, 7, v2
	global_load_dword v3, v1, s[2:3]
	s_add_u32 s2, s2, 0x2000
	s_addc_u32 s3, s3, 0
	global_load_dword v3, v1, s[2:3]
	s_add_u32 s2, s2, 0x2000
	s_addc_u32 s3, s3, 0
	global_load_dword v3, v1, s[2:3]
	s_add_u32 s2, s2, 0x2000
	s_addc_u32 s3, s3, 0
	global_load_dword v3, v1, s[2:3]
	s_add_u32 s2, s2, 0x2000
	s_addc_u32 s3, s3, 0
	global_load_dword v3, v1, s[2:3]
	s_add_u32 s2, s2, 0x2000
	s_addc_u32 s3, s3, 0
	global_load_dword v3, v1, s[2:3]
	s_add_u32 s2, s2, 0x2000
	s_addc_u32 s3, s3, 0
	global_load_dword v3, v1, s[2:3]
	s_add_u32 s2, s2, 0x2000
	s_addc_u32 s3, s3, 0
	global_load_dword v3, v1, s[2:3]
